# wide u^T loads placed in hw0 slack + sample rebalance (m17_rebal808)
# speedup vs baseline: 1.0072x; 1.0067x over previous
.LBB0_827:
	s_or_b64 exec, exec, s[4:5]
	v_and_b32_e32 v46, 7, v47
	v_lshlrev_b32_e32 v0, 6, v46
	global_load_dwordx4 v[64:67], v0, s[26:27] offset:48
	global_load_dwordx4 v[68:71], v0, s[26:27] offset:32
	global_load_dwordx4 v[72:75], v0, s[26:27] offset:16
	global_load_dwordx4 v[76:79], v0, s[26:27]
	s_ashr_i32 s47, s46, 3
	s_and_b32 s35, s46, 7
	s_lshl_b32 s50, s47, 11
	s_sub_i32 s14, s50, 64
	s_lshl_b32 s4, s35, 8
	s_add_u32 s48, s18, s4
	s_addc_u32 s49, s19, 0
	s_lshl_b32 s34, s47, 8
	s_or_b32 s12, s34, s35
	v_lshlrev_b32_e32 v20, 3, v47
	s_ashr_i32 s13, s12, 31
	v_and_b32_e32 v0, 0x78, v20
	s_lshl_b64 s[4:5], s[12:13], 14
	v_lshlrev_b32_e32 v124, 1, v0
	s_add_u32 s4, s20, s4
	v_ashrrev_i32_e32 v28, 4, v47
	v_lshl_add_u64 v[126:127], s[48:49], 0, v[124:125]
	s_addc_u32 s5, s21, s5
	v_cmp_lt_i32_e64 s[16:17], 63, v28
	s_and_saveexec_b64 s[6:7], s[16:17]
	s_xor_b64 s[6:7], exec, s[6:7]
	v_add_u32_e32 v0, s14, v28
	v_mad_i64_i32 v[0:1], s[8:9], v0, s60, v[126:127]
	s_or_saveexec_b64 s[6:7], s[6:7]
	v_lshl_add_u64 v[12:13], s[4:5], 0, v[124:125]
	v_ashrrev_i32_e32 v29, 31, v28
	s_xor_b64 exec, exec, s[6:7]
	v_lshlrev_b64 v[0:1], 8, v[28:29]
	v_lshl_add_u64 v[0:1], v[12:13], 0, v[0:1]
	s_or_b64 exec, exec, s[6:7]
	global_load_dwordx4 v[0:3], v[0:1], off
	v_add_u32_e32 v37, 0x200, v47
	v_ashrrev_i32_e32 v30, 4, v37
	v_cmp_lt_i32_e64 s[4:5], 63, v30
	s_and_saveexec_b64 s[6:7], s[4:5]
	s_xor_b64 s[6:7], exec, s[6:7]
	v_add_u32_e32 v4, s14, v30
	v_mad_i64_i32 v[4:5], s[8:9], v4, s60, v[126:127]
	s_or_saveexec_b64 s[6:7], s[6:7]
	v_ashrrev_i32_e32 v31, 31, v30
	s_xor_b64 exec, exec, s[6:7]
	v_lshlrev_b64 v[4:5], 8, v[30:31]
	v_lshl_add_u64 v[4:5], v[12:13], 0, v[4:5]
	s_or_b64 exec, exec, s[6:7]
	global_load_dwordx4 v[4:7], v[4:5], off
	v_add_u32_e32 v8, 0x400, v47
	v_ashrrev_i32_e32 v32, 4, v8
	v_cmp_lt_i32_e64 s[6:7], 63, v32
	s_and_saveexec_b64 s[8:9], s[6:7]
	s_xor_b64 s[8:9], exec, s[8:9]
	v_add_u32_e32 v8, s14, v32
	v_mad_i64_i32 v[8:9], s[10:11], v8, s60, v[126:127]
	s_or_saveexec_b64 s[8:9], s[8:9]
	v_ashrrev_i32_e32 v33, 31, v32
	s_xor_b64 exec, exec, s[8:9]
	v_lshlrev_b64 v[8:9], 8, v[32:33]
	v_lshl_add_u64 v[8:9], v[12:13], 0, v[8:9]
	s_or_b64 exec, exec, s[8:9]
	global_load_dwordx4 v[8:11], v[8:9], off
	v_add_u32_e32 v14, 0x600, v47
	v_ashrrev_i32_e32 v34, 4, v14
	v_cmp_lt_i32_e64 s[8:9], 63, v34
	s_and_saveexec_b64 s[10:11], s[8:9]
	s_xor_b64 s[10:11], exec, s[10:11]
	v_add_u32_e32 v12, s14, v34
	v_mad_i64_i32 v[14:15], s[14:15], v12, s60, v[126:127]
	s_or_saveexec_b64 s[10:11], s[10:11]
	v_ashrrev_i32_e32 v35, 31, v34
	s_xor_b64 exec, exec, s[10:11]
	v_lshlrev_b64 v[14:15], 8, v[34:35]
	v_lshl_add_u64 v[14:15], v[12:13], 0, v[14:15]
	s_or_b64 exec, exec, s[10:11]
	s_lshl_b32 s14, s35, 7
	v_ashrrev_i32_e32 v36, 3, v47
	s_lshl_b64 s[10:11], s[12:13], 13
	s_add_u32 s10, s22, s10
	v_lshlrev_b32_e32 v44, 6, v36
	s_addc_u32 s11, s23, s11
	v_ashrrev_i32_e32 v45, 31, v44
	s_waitcnt vmcnt(0)
	v_and_b32_e32 v51, 56, v20
	v_and_b32_e32 v24, 64, v20
	v_add_u32_e32 v151, s50, v28
	v_mov_b64_e32 v[20:21], s[18:19]
	v_add_u32_e32 v172, s50, v30
	v_lshl_add_u64 v[16:17], v[44:45], 1, s[10:11]
	v_mad_i64_i32 v[22:23], s[10:11], v151, s60, v[20:21]
	s_lshl_b32 s36, s14, 1
	v_mad_i64_i32 v[20:21], s[10:11], v172, s60, v[20:21]
	v_lshl_add_u64 v[22:23], v[22:23], 0, s[36:37]
	v_lshlrev_b32_e32 v38, 1, v24
	v_mov_b32_e32 v39, v125
	v_lshl_add_u64 v[20:21], v[20:21], 0, s[36:37]
	v_lshlrev_b32_e32 v42, 4, v46
	v_mov_b32_e32 v43, v125
	v_lshl_add_u64 v[22:23], v[22:23], 0, v[38:39]
	v_lshlrev_b32_e32 v40, 1, v51
	v_mov_b32_e32 v41, v125
	v_lshl_add_u64 v[20:21], v[20:21], 0, v[38:39]
	v_lshl_add_u64 v[16:17], v[16:17], 0, v[42:43]
	v_lshl_add_u64 v[22:23], v[22:23], 0, v[40:41]
	v_lshl_add_u64 v[20:21], v[20:21], 0, v[40:41]
	global_load_dwordx4 v[12:15], v[14:15], off
	v_lshrrev_b32_e32 v39, 1, v47
	global_load_dwordx4 v[16:19], v[16:17], off
	s_nop 0
	global_load_dwordx4 v[24:27], v[22:23], off offset:2048
	s_nop 0
	global_load_dwordx4 v[20:23], v[20:21], off offset:2048
	v_and_b32_e32 v43, 0x60, v39
	v_and_b32_e32 v48, 31, v47
	v_bfe_u32 v49, v47, 5, 1
	v_or_b32_e32 v50, v43, v48
	v_cmp_gt_u32_e64 s[10:11], s61, v47
	v_lshlrev_b32_e32 v128, 3, v49
	s_and_saveexec_b64 s[14:15], s[10:11]
	s_cbranch_execz .LBB0_845
	v_lshrrev_b32_e32 v39, 1, v50
	v_or_b32_e32 v39, s50, v39
	v_mov_b64_e32 v[52:53], s[18:19]
	v_mad_i64_i32 v[52:53], s[52:53], v39, s60, v[52:53]
	v_lshlrev_b32_e32 v39, 7, v47
	v_lshl_add_u64 v[52:53], v[52:53], 0, s[36:37]
	v_and_b32_e32 v54, 0x80, v39
	v_mov_b32_e32 v55, v125
	v_lshl_add_u64 v[52:53], v[52:53], 0, v[54:55]
	v_mov_b32_e32 v129, v125
	v_lshl_add_u64 v[52:53], v[52:53], 0, v[128:129]
	v_lshl_add_u64 v[54:55], v[52:53], 0, s[38:39]
	v_and_b32_e32 v39, 32, v149
	v_lshrrev_b32_e32 v39, 2, v39
	v_mul_u32_u24_e32 v39, 7, v39
	v_add_co_u32_e32 v54, vcc, v39, v54
	s_nop 1
	v_addc_co_u32_e32 v55, vcc, 0, v55, vcc
	global_load_dwordx4 v[130:133], v[54:55], off
	global_load_dwordx4 v[134:137], v[54:55], off offset:16
	global_load_dwordx4 v[138:141], v[54:55], off offset:32
	global_load_dwordx4 v[142:145], v[54:55], off offset:48

.Lmy_scan_nz:
	s_and_saveexec_b64 s[50:51], s[10:11]
	s_cbranch_execz .LBB0_865
	s_nop 3
	v_permlane32_swap_b32_e32 v130, v132
	v_permlane32_swap_b32_e32 v131, v133
	v_permlane32_swap_b32_e32 v134, v136
	v_permlane32_swap_b32_e32 v135, v137
	v_permlane32_swap_b32_e32 v138, v140
	v_permlane32_swap_b32_e32 v139, v141
	v_permlane32_swap_b32_e32 v142, v144
	v_permlane32_swap_b32_e32 v143, v145
	v_lshlrev_b32_e32 v32, 16, v130
	v_and_b32_e32 v33, 0xffff0000, v130
	v_lshlrev_b32_e32 v34, 16, v131
	v_and_b32_e32 v35, 0xffff0000, v131
	v_lshlrev_b32_e32 v48, 16, v132
	v_and_b32_e32 v49, 0xffff0000, v132
	v_lshlrev_b32_e32 v50, 16, v133
	v_and_b32_e32 v51, 0xffff0000, v133
	v_lshlrev_b32_e32 v36, 16, v134
	v_and_b32_e32 v37, 0xffff0000, v134
	v_lshlrev_b32_e32 v38, 16, v135
	v_and_b32_e32 v39, 0xffff0000, v135
	v_lshlrev_b32_e32 v52, 16, v136
	v_and_b32_e32 v53, 0xffff0000, v136
	v_lshlrev_b32_e32 v54, 16, v137
	v_and_b32_e32 v55, 0xffff0000, v137
	v_lshlrev_b32_e32 v40, 16, v138
	v_and_b32_e32 v41, 0xffff0000, v138
	v_lshlrev_b32_e32 v42, 16, v139
	v_and_b32_e32 v43, 0xffff0000, v139
	v_lshlrev_b32_e32 v56, 16, v140
	v_and_b32_e32 v57, 0xffff0000, v140
	v_lshlrev_b32_e32 v58, 16, v141
	v_and_b32_e32 v59, 0xffff0000, v141
	v_lshlrev_b32_e32 v44, 16, v142
	v_and_b32_e32 v45, 0xffff0000, v142
	v_lshlrev_b32_e32 v46, 16, v143
	v_and_b32_e32 v47, 0xffff0000, v143
	v_lshlrev_b32_e32 v60, 16, v144
	v_and_b32_e32 v61, 0xffff0000, v144
	v_lshlrev_b32_e32 v62, 16, v145
	v_and_b32_e32 v63, 0xffff0000, v145

.LBB0_880:
	s_or_b64 exec, exec, s[52:53]
	ds_read_b128 v[116:119], v183 offset:44128
	ds_read_b128 v[214:217], v183 offset:48736
	s_and_b64 vcc, exec, s[50:51]
	s_waitcnt lgkmcnt(1)
	v_mfma_f32_32x32x16_bf16 v[0:15], v[116:119], v[120:123], v[0:15]
	s_waitcnt lgkmcnt(0)
	v_mfma_f32_32x32x16_bf16 v[16:31], v[214:217], v[120:123], v[16:31]
	s_cbranch_vccz .LBB0_899
	s_waitcnt vmcnt(8)
	ds_write_b128 v129, v[80:83]
	s_waitcnt vmcnt(7)
	ds_write_b128 v173, v[84:87]
	s_waitcnt vmcnt(6)
	ds_write_b128 v174, v[92:95]
	s_waitcnt vmcnt(5)
	ds_write_b128 v175, v[104:107]
	s_and_saveexec_b64 s[52:53], s[10:11]
	s_cbranch_execz .LBB0_868
	v_add_u32_e32 v230, s47, v205
	v_mov_b64_e32 v[232:233], s[18:19]
	v_mad_i64_i32 v[232:233], s[34:35], v230, s60, v[232:233]
	v_lshl_add_u64 v[232:233], v[232:233], 0, s[36:37]
	v_lshl_add_u64 v[232:233], v[232:233], 0, v[124:125]
	v_lshlrev_b32_e32 v230, 1, v148
	v_mov_b32_e32 v231, v125
	v_lshl_add_u64 v[232:233], v[232:233], 0, v[230:231]
	v_lshl_add_u64 v[230:231], v[232:233], 0, s[38:39]
	v_and_b32_e32 v232, 32, v149
	v_lshrrev_b32_e32 v232, 2, v232
	v_mul_u32_u24_e32 v232, 7, v232
	v_add_co_u32_e32 v230, vcc, v232, v230
	s_nop 1
	v_addc_co_u32_e32 v231, vcc, 0, v231, vcc
	global_load_dwordx4 v[130:133], v[230:231], off
	global_load_dwordx4 v[134:137], v[230:231], off offset:16
	global_load_dwordx4 v[138:141], v[230:231], off offset:32
	global_load_dwordx4 v[142:145], v[230:231], off offset:48

.LBB0_919:
	s_add_i32 s28, s33, 0xffffff7b
	s_sub_i32 s4, 0x108, s33
	s_cmpk_lt_u32 s28, 0x83
	s_cselect_b32 s8, s4, 0
	s_sub_i32 s24, s3, s8
	s_cmp_ge_i32 s3, s8
	s_cselect_b32 s6, s24, 0x400
	s_cmpk_lt_i32 s6, 0x400
	s_cselect_b64 s[4:5], -1, 0
	s_movk_i32 s99, 0x400
	s_cmpk_lg_i32 s30, 0x100
	s_cbranch_scc1 .Lmy_samp_noovr
	s_cmpk_lt_u32 s2, 136
	s_cbranch_scc1 .Lmy_samp_bc
	s_sub_i32 s6, s2, 136
	s_movk_i32 s98, 120
	s_movk_i32 s99, 808
	s_branch .Lmy_samp_set
.Lmy_samp_bc:
	s_cmpk_lt_u32 s2, 64
	s_cbranch_scc1 .Lmy_samp_c
	s_sub_i32 s6, s2, 64
	s_addk_i32 s6, 808
	s_movk_i32 s98, 72
	s_movk_i32 s99, 1024
	s_branch .Lmy_samp_set
.Lmy_samp_c:
	s_add_i32 s6, s2, 1024
	s_movk_i32 s98, 64
	s_movk_i32 s99, 0x400
.Lmy_samp_set:
	s_cmp_lt_i32 s6, s99
	s_cselect_b64 s[4:5], -1, 0
	s_cselect_b32 s6, s6, 0x400
	s_mov_b32 s24, s6
	s_mov_b32 s100, s6
.Lmy_samp_noovr:
	s_cmpk_gt_i32 s6, 0x3ff
	s_cbranch_scc1 .LBB0_921
	v_mov_b32_e32 v2, v170
	s_waitcnt lgkmcnt(0)
	s_load_dwordx2 s[10:11], s[0:1], 0x20
	s_ashr_i32 s7, s6, 31
	v_ashrrev_i32_e32 v0, 2, v2
	v_and_b32_e32 v0, -8, v0
	s_lshl_b64 s[6:7], s[6:7], 16
	v_ashrrev_i32_e32 v1, 31, v0
	s_waitcnt lgkmcnt(0)
	s_add_u32 s6, s10, s6
	s_addc_u32 s7, s11, s7
	v_lshlrev_b64 v[0:1], 9, v[0:1]
	v_lshlrev_b32_e32 v2, 4, v2
	v_lshl_add_u64 v[0:1], s[6:7], 0, v[0:1]
	v_and_b32_e32 v2, 0x1f0, v2
	v_mov_b32_e32 v3, 0
	v_lshl_add_u64 v[0:1], v[0:1], 0, v[2:3]
	global_load_dwordx4 v[72:75], v[0:1], off nt
	global_load_dwordx4 v[68:71], v[0:1], off offset:512 nt
	global_load_dwordx4 v[64:67], v[0:1], off offset:1024 nt
	global_load_dwordx4 v[60:63], v[0:1], off offset:1536 nt
	global_load_dwordx4 v[56:59], v[0:1], off offset:2048 nt
	global_load_dwordx4 v[52:55], v[0:1], off offset:2560 nt
	global_load_dwordx4 v[48:51], v[0:1], off offset:3072 nt
	global_load_dwordx4 v[44:47], v[0:1], off offset:3584 nt
.LBB0_921:
	s_andn2_b64 vcc, exec, s[4:5]
	s_cbranch_vccnz .LBB0_958
	s_waitcnt lgkmcnt(0)
	s_sub_i32 s12, s33, s8
	s_load_dwordx2 s[14:15], s[0:1], 0x50
	s_load_dwordx4 s[4:7], s[0:1], 0x80
	s_load_dwordx4 s[8:11], s[0:1], 0x18
	s_load_dwordx2 s[16:17], s[0:1], 0x38
	s_load_dwordx2 s[18:19], s[0:1], 0xd0
	s_load_dwordx2 s[20:21], s[0:1], 0x90
	s_waitcnt lgkmcnt(0)
	s_add_u32 s22, s4, 0x4758000
	s_addc_u32 s23, s5, 0
	s_ashr_i32 s25, s24, 31
	s_lshl_b64 s[24:25], s[24:25], 16
	s_add_u32 s4, s4, s24
	s_addc_u32 s5, s5, s25
	s_add_u32 s24, s4, 0x4bd8000
	s_addc_u32 s25, s5, 0
	s_ashr_i32 s13, s12, 31
	s_max_u32 s4, s28, 0x83
	s_lshl_b64 s[26:27], s[12:13], 16
	s_sub_i32 s13, s28, s4
	s_mul_i32 s33, s33, 3
	s_lshl_b32 s4, s4, 1
	v_mbcnt_lo_u32_b32 v0, -1, 0
	s_sub_i32 s33, s33, s4
	v_mbcnt_hi_u32_b32 v149, -1, v0
	s_waitcnt vmcnt(0)
	v_mov_b64_e32 v[0:1], v[44:45]
	v_mov_b64_e32 v[4:5], v[48:49]
	v_mov_b64_e32 v[8:9], v[52:53]
	v_mov_b64_e32 v[12:13], v[56:57]
	v_mov_b64_e32 v[16:17], v[60:61]
	v_mov_b64_e32 v[20:21], v[64:65]
	v_mov_b64_e32 v[24:25], v[68:69]
	v_mov_b64_e32 v[28:29], v[72:73]
	s_addk_i32 s33, 0xfef6
	s_mov_b32 s29, 0
	v_mov_b32_e32 v141, 0
	s_movk_i32 s50, 0xc0
	s_mov_b32 s51, 0x55555556
	s_movk_i32 s52, 0x1800
	s_movk_i32 s53, 0x3000
	s_mov_b64 s[36:37], 0x3000
	s_mov_b64 s[38:39], 0x6000
	s_mov_b64 s[40:41], 0x9000
	s_mov_b32 s54, 0x800000
	s_movk_i32 s55, 0x80
	v_mov_b32_e32 v147, 0x358637bd
	v_mov_b32_e32 v151, 0x3db504f3
	v_mov_b32_e32 v153, 0x1000
	v_mov_b32_e32 v158, 0x800
	v_mov_b64_e32 v[2:3], v[46:47]
	v_mov_b64_e32 v[6:7], v[50:51]
	v_mov_b64_e32 v[10:11], v[54:55]
	v_mov_b64_e32 v[14:15], v[58:59]
	v_mov_b64_e32 v[18:19], v[62:63]
	v_mov_b64_e32 v[22:23], v[66:67]
	v_mov_b64_e32 v[26:27], v[70:71]
	v_mov_b64_e32 v[30:31], v[74:75]
	s_cmpk_lg_i32 s30, 0x100
	s_cbranch_scc1 .Lmy_samp_noovr2
	s_mov_b32 s12, s98
	s_mov_b32 s13, 0
	s_mov_b32 s33, s98
	s_mov_b32 s3, s100
	s_lshl_b32 s26, s98, 16
	s_mov_b32 s27, 0
	s_lshl_b32 s24, s100, 16
	s_add_u32 s24, s22, s24
	s_addc_u32 s25, s23, 0
	s_add_u32 s24, s24, 0x480000
	s_addc_u32 s25, s25, 0
.Lmy_samp_noovr2:
	s_branch .LBB0_924
.Lmy_samp_scan:
	s_movk_i32 s33, 0xc0
	s_mov_b32 s3, 0
	s_branch .LBB0_919
.LBB0_923:
	s_or_b64 exec, exec, s[4:5]
	s_add_u32 s24, s24, s26
	s_waitcnt lgkmcnt(0)
	s_barrier
	s_addc_u32 s25, s25, s27
	s_add_i32 s3, s3, s12
	s_add_i32 s4, s13, s3
	s_waitcnt vmcnt(8)
	v_mov_b64_e32 v[46:47], v[2:3]
	v_mov_b64_e32 v[50:51], v[6:7]
	v_mov_b64_e32 v[54:55], v[10:11]
	v_mov_b64_e32 v[58:59], v[14:15]
	v_mov_b64_e32 v[62:63], v[18:19]
	v_mov_b64_e32 v[66:67], v[22:23]
	v_mov_b64_e32 v[70:71], v[26:27]
	v_mov_b64_e32 v[74:75], v[30:31]
	s_cmp_lt_i32 s4, s99
	v_mov_b64_e32 v[44:45], v[0:1]
	v_mov_b64_e32 v[48:49], v[4:5]
	v_mov_b64_e32 v[52:53], v[8:9]
	v_mov_b64_e32 v[56:57], v[12:13]
	v_mov_b64_e32 v[60:61], v[16:17]
	v_mov_b64_e32 v[64:65], v[20:21]
	v_mov_b64_e32 v[68:69], v[24:25]
	v_mov_b64_e32 v[72:73], v[28:29]
	s_cbranch_scc0 .LBB0_958
.LBB0_924:
	s_add_i32 s4, s33, s3
	v_mov_b32_e32 v143, v170
	s_cmp_lt_i32 s4, s99
	s_cselect_b32 s28, s4, -1
	s_mov_b32 s100, s28
	s_mov_b32 s101, 0
	v_ashrrev_i32_e32 v164, 5, v143
	v_lshlrev_b32_e32 v144, 3, v164
	v_and_b32_e32 v159, 31, v143
	v_ashrrev_i32_e32 v145, 31, v144

.LBB0_948:
	s_or_b64 exec, exec, s[46:47]
	v_and_b32_e32 v76, 0xffffffe0, v143
	s_waitcnt lgkmcnt(0)
	s_barrier
	v_add_u32_e32 v80, 0, v76
	s_waitcnt vmcnt(10)
	s_cmp_lt_i32 s100, 0
	s_cbranch_scc1 .Lmy_nopf
	s_lshl_b64 s[4:5], s[100:101], 16
	s_add_u32 s4, s10, s4
	s_addc_u32 s5, s11, s5
	v_lshlrev_b64 v[174:175], 9, v[144:145]
	v_lshl_add_u64 v[174:175], s[4:5], 0, v[174:175]
	v_lshlrev_b32_e32 v176, 4, v159
	v_mov_b32_e32 v177, 0
	v_lshl_add_u64 v[174:175], v[174:175], 0, v[176:177]
	global_load_dwordx4 v[28:31], v[174:175], off nt
	global_load_dwordx4 v[24:27], v[174:175], off offset:512 nt
	global_load_dwordx4 v[20:23], v[174:175], off offset:1024 nt
	global_load_dwordx4 v[16:19], v[174:175], off offset:1536 nt
	global_load_dwordx4 v[12:15], v[174:175], off offset:2048 nt
	global_load_dwordx4 v[8:11], v[174:175], off offset:2560 nt
	global_load_dwordx4 v[4:7], v[174:175], off offset:3072 nt
	global_load_dwordx4 v[0:3], v[174:175], off offset:3584 nt
	s_branch .Lmy_pfj
